# gdn_prep record output stage: all LDS reads issued before one wait (was 13 exposed waits)
# speedup vs baseline: 1.0038x; 1.0038x over previous
; DI unsigned pk2(float lo, float hi) { f32x2 v = {lo, hi}; bf16x2_t r = __builtin_convertvector(v, bf16x2_t); return __builtin_bit_cast(unsigned, r); }
; DI int PERM(int p) { return (p & ~31) + 16 * ((p >> 2) & 1) + 4 * ((p >> 3) & 3) + (p & 3); }
; DI void phase_gdn_prep(const Params& p, int l, char* smem) {
;     ...
;         {
;             const int r = tid >> 2, part = tid & 3;
;             u32x4 v0, v1, w0, w1;
; #pragma unroll
;             for (int j = 0; j < 8; ++j) {
;                 const int p0 = part * 16 + 2 * j, p1 = p0 + 1;
;                 const unsigned a = pk2(sk[r * 65 + PERM(p0)], sk[r * 65 + PERM(p1)]);
;                 const unsigned c = pk2(sv[p0 * 65 + r], sv[p1 * 65 + r]);
;                 if (j < 4) { v0[j] = a; w0[j] = c; } else { v1[j - 4] = a; w1[j - 4] = c; }
;             }
;             *(u32x4*)(rec + (r * 64 + part * 16) * 2) = v0; *(u32x4*)(rec + (r * 64 + part * 16 + 8) * 2) = v1;
;             *(u32x4*)(rec + 32768 + (r * 64 + part * 16) * 2) = w0; *(u32x4*)(rec + 32768 + (r * 64 + part * 16 + 8) * 2) = w1;
;         }
.LBB0_263:
	s_add_u32 s4, s88, 0x8000
	s_addc_u32 s5, s89, 0
	s_andn2_b64 vcc, exec, s[90:91]
	s_mov_b32 s86, s30
	ds_read_b32 v76, v171 offset:33280
	v_add_u32_e32 v187, 0x8000, v172
	ds_read2_b32 v[200:201], v187 offset0:128 offset1:193
	ds_read2_b32 v[202:203], v179 offset0:64 offset1:80
	ds_read2_b32 v[204:205], v180 offset0:64 offset1:80
	v_add_u32_e32 v187, 0x8400, v172
	ds_read2_b32 v[206:207], v187 offset0:2 offset1:132
	ds_read2_b32 v[208:209], v181 offset0:64 offset1:80
	ds_read2_b32 v[230:231], v182 offset0:64 offset1:80
	ds_read_b32 v185, v171 offset:34320
	v_add_u32_e32 v187, 0x8600, v172
	ds_read2_b32 v[232:233], v187 offset0:69 offset1:134
	v_add_u32_e32 v187, 0x8800, v172
	ds_read2_b32 v[234:235], v187 offset0:71 offset1:136
	ds_read2_b32 v[236:237], v183 offset0:64 offset1:80
	ds_read2_b32 v[238:239], v184 offset0:64 offset1:80
	v_add_u32_e32 v187, 0x8a00, v172
	ds_read2_b32 v[240:241], v187 offset0:73 offset1:138
	ds_read_b32 v186, v158 offset:16640
	ds_read_b32 v188, v159 offset:16640
	v_add_u32_e32 v187, 0x8c00, v172
	ds_read2_b32 v[244:245], v187 offset0:75 offset1:140
	v_add_u32_e32 v187, 0x8e00, v172
	ds_read2_b32 v[254:255], v187 offset0:77 offset1:142
	ds_read_b32 v191, v160 offset:16704
	ds_read_b32 v243, v161 offset:16704
	s_waitcnt lgkmcnt(0)
	v_cvt_pk_bf16_f32 v36, v76, v200
	v_cvt_pk_bf16_f32 v58, v202, v204
	v_cvt_pk_bf16_f32 v60, v203, v205
	v_cvt_pk_bf16_f32 v37, v201, v206
	v_cvt_pk_bf16_f32 v59, v208, v230
	v_cvt_pk_bf16_f32 v38, v185, v207
	v_cvt_pk_bf16_f32 v61, v209, v231
	v_cvt_pk_bf16_f32 v39, v232, v233
	v_cvt_pk_bf16_f32 v192, v234, v235
	v_cvt_pk_bf16_f32 v196, v236, v238
	v_cvt_pk_bf16_f32 v193, v240, v241
	v_cvt_pk_bf16_f32 v197, v186, v188
	v_cvt_pk_bf16_f32 v194, v244, v245
	v_cvt_pk_bf16_f32 v198, v237, v239
	v_cvt_pk_bf16_f32 v195, v254, v255
	v_cvt_pk_bf16_f32 v199, v191, v243
	v_lshl_add_u64 v[186:187], s[88:89], 0, v[42:43]
	global_store_dwordx4 v[186:187], v[58:61], off
	global_store_dwordx4 v[186:187], v[196:199], off offset:16
	s_nop 0
	v_lshl_add_u64 v[58:59], s[4:5], 0, v[42:43]
	global_store_dwordx4 v[58:59], v[36:39], off
	s_nop 1
	v_lshl_add_u64 v[36:37], s[4:5], 0, v[44:45]
	global_store_dwordx4 v[36:37], v[192:195], off
	s_barrier
	s_cbranch_vccz .LBB0_347
